# P1: the k_rope tile (pn 15, 64 real columns) runs a copy of the main loop without the MFMAs of the zero-padded accumulator quads; waves whose strip is all padding skip the rest
# speedup vs baseline: 1.0073x; 1.0073x over previous
.LBB0_216:
	s_ashr_i32 s51, s50, 31
	s_lshl_b64 s[10:11], s[50:51], 20
	s_add_u32 s52, s22, s10
	s_addc_u32 s53, s23, s11
	s_and_b64 s[10:11], s[8:9], exec
	s_cselect_b32 s45, s53, s77
	s_cselect_b32 s51, s52, s76
	s_ashr_i32 s49, s48, 31
	s_lshl_b64 s[10:11], s[48:49], 20
	s_add_u32 s54, s72, s10
	s_addc_u32 s55, s73, s11
	s_and_b64 s[10:11], s[8:9], exec
	s_cselect_b32 s49, s55, s79
	s_cselect_b32 s75, s54, s78
	s_add_u32 s76, s76, 0x80080
	s_addc_u32 s77, s77, 0
	s_add_u32 vcc_lo, s78, 0x100
	v_mov_b32_e32 v0, 0
	s_addc_u32 vcc_hi, s79, 0
	s_mov_b32 s10, -2
	s_waitcnt lgkmcnt(0)
	v_mov_b32_e32 v1, v0
	v_mov_b32_e32 v2, v0
	v_mov_b32_e32 v3, v0
	v_mov_b32_e32 v4, v0
	v_mov_b32_e32 v5, v0
	v_mov_b32_e32 v6, v0
	v_mov_b32_e32 v7, v0
	v_mov_b32_e32 v8, v0
	v_mov_b32_e32 v9, v0
	v_mov_b32_e32 v10, v0
	v_mov_b32_e32 v11, v0
	v_mov_b32_e32 v16, v0
	v_mov_b32_e32 v17, v0
	v_mov_b32_e32 v18, v0
	v_mov_b32_e32 v19, v0
	v_mov_b32_e32 v24, v0
	v_mov_b32_e32 v25, v0
	v_mov_b32_e32 v26, v0
	v_mov_b32_e32 v27, v0
	v_mov_b32_e32 v32, v0
	v_mov_b32_e32 v33, v0
	v_mov_b32_e32 v34, v0
	v_mov_b32_e32 v35, v0
	v_mov_b32_e32 v40, v0
	v_mov_b32_e32 v41, v0
	v_mov_b32_e32 v42, v0
	v_mov_b32_e32 v43, v0
	v_mov_b32_e32 v48, v0
	v_mov_b32_e32 v49, v0
	v_mov_b32_e32 v50, v0
	v_mov_b32_e32 v51, v0
	v_mov_b32_e32 v12, v0
	v_mov_b32_e32 v13, v0
	v_mov_b32_e32 v14, v0
	v_mov_b32_e32 v15, v0
	v_mov_b32_e32 v20, v0
	v_mov_b32_e32 v21, v0
	v_mov_b32_e32 v22, v0
	v_mov_b32_e32 v23, v0
	v_mov_b32_e32 v28, v0
	v_mov_b32_e32 v29, v0
	v_mov_b32_e32 v30, v0
	v_mov_b32_e32 v31, v0
	v_mov_b32_e32 v36, v0
	v_mov_b32_e32 v37, v0
	v_mov_b32_e32 v38, v0
	v_mov_b32_e32 v39, v0
	v_mov_b32_e32 v44, v0
	v_mov_b32_e32 v45, v0
	v_mov_b32_e32 v46, v0
	v_mov_b32_e32 v47, v0
	v_mov_b32_e32 v52, v0
	v_mov_b32_e32 v53, v0
	v_mov_b32_e32 v54, v0
	v_mov_b32_e32 v55, v0
	v_mov_b32_e32 v56, v0
	v_mov_b32_e32 v57, v0
	v_mov_b32_e32 v58, v0
	v_mov_b32_e32 v59, v0
	v_mov_b32_e32 v60, v0
	v_mov_b32_e32 v61, v0
	v_mov_b32_e32 v62, v0
	v_mov_b32_e32 v63, v0
	v_mov_b32_e32 v64, v0
	v_mov_b32_e32 v65, v0
	v_mov_b32_e32 v66, v0
	v_mov_b32_e32 v67, v0
	v_mov_b32_e32 v68, v0
	v_mov_b32_e32 v69, v0
	v_mov_b32_e32 v70, v0
	v_mov_b32_e32 v71, v0
	v_mov_b32_e32 v72, v0
	v_mov_b32_e32 v73, v0
	v_mov_b32_e32 v74, v0
	v_mov_b32_e32 v75, v0
	v_mov_b32_e32 v80, v0
	v_mov_b32_e32 v81, v0
	v_mov_b32_e32 v82, v0
	v_mov_b32_e32 v83, v0
	v_mov_b32_e32 v88, v0
	v_mov_b32_e32 v89, v0
	v_mov_b32_e32 v90, v0
	v_mov_b32_e32 v91, v0
	v_mov_b32_e32 v96, v0
	v_mov_b32_e32 v97, v0
	v_mov_b32_e32 v98, v0
	v_mov_b32_e32 v99, v0
	v_mov_b32_e32 v104, v0
	v_mov_b32_e32 v105, v0
	v_mov_b32_e32 v106, v0
	v_mov_b32_e32 v107, v0
	v_mov_b32_e32 v112, v0
	v_mov_b32_e32 v113, v0
	v_mov_b32_e32 v114, v0
	v_mov_b32_e32 v115, v0
	v_mov_b32_e32 v76, v0
	v_mov_b32_e32 v77, v0
	v_mov_b32_e32 v78, v0
	v_mov_b32_e32 v79, v0
	v_mov_b32_e32 v84, v0
	v_mov_b32_e32 v85, v0
	v_mov_b32_e32 v86, v0
	v_mov_b32_e32 v87, v0
	v_mov_b32_e32 v92, v0
	v_mov_b32_e32 v93, v0
	v_mov_b32_e32 v94, v0
	v_mov_b32_e32 v95, v0
	v_mov_b32_e32 v100, v0
	v_mov_b32_e32 v101, v0
	v_mov_b32_e32 v102, v0
	v_mov_b32_e32 v103, v0
	v_mov_b32_e32 v108, v0
	v_mov_b32_e32 v109, v0
	v_mov_b32_e32 v110, v0
	v_mov_b32_e32 v111, v0
	v_mov_b32_e32 v116, v0
	v_mov_b32_e32 v117, v0
	v_mov_b32_e32 v118, v0
	v_mov_b32_e32 v119, v0
	v_mov_b32_e32 v120, v0
	v_mov_b32_e32 v121, v0
	v_mov_b32_e32 v122, v0
	v_mov_b32_e32 v123, v0
	v_mov_b32_e32 v124, v0
	v_mov_b32_e32 v125, v0
	v_mov_b32_e32 v126, v0
	v_mov_b32_e32 v127, v0
	s_cmp_eq_u32 s16, 15
	s_cbranch_scc1 .Lkr_loop

.Lkr_ret:
	s_and_b64 vcc, exec, s[40:41]
	s_cbranch_vccnz .LBB0_221
	v_lshl_add_u32 v160, s74, 8, v147
	s_cmp_gt_i32 s16, 11
	s_mov_b64 s[74:75], -1
	s_cbranch_scc1 .LBB0_222

.Lkr_loop:
	ds_read_b128 v[128:131], v171
	ds_read_b128 v[132:135], v171 offset:1024
	ds_read_b128 v[160:163], v171 offset:2048
	ds_read_b128 v[164:167], v171 offset:3072
	ds_read_b128 v[176:179], v172
	ds_read_b128 v[180:183], v172 offset:1024
	ds_read_b128 v[184:187], v172 offset:2048
	ds_read_b128 v[188:191], v172 offset:3072
	s_add_u32 s11, s76, 0xfff80080
	s_addc_u32 s60, s77, -1
	s_cmp_eq_u32 s10, 28
	s_cselect_b32 s81, s45, s60
	s_cselect_b32 s80, s51, s11
	s_cselect_b32 s79, s49, vcc_hi
	s_cselect_b32 s78, s75, vcc_lo
	v_lshl_add_u64 v[168:169], s[76:77], 0, v[152:153]
	s_add_i32 m0, s82, 0xc000
	ds_read_b128 v[192:195], v173
	ds_read_b128 v[196:199], v173 offset:1024
	ds_read_b128 v[200:203], v173 offset:2048
	ds_read_b128 v[206:209], v173 offset:3072
	ds_read_b128 v[210:213], v173 offset:4096
	ds_read_b128 v[214:217], v173 offset:5120
	ds_read_b128 v[218:221], v173 offset:6144
	ds_read_b128 v[222:225], v173 offset:7168
	global_load_lds_dwordx4 v[168:169], off
	v_lshl_add_u64 v[168:169], s[76:77], 0, v[154:155]
	s_add_i32 m0, s82, 0xe000
	s_nop 0
	global_load_lds_dwordx4 v[168:169], off
	s_waitcnt vmcnt(8)
	s_waitcnt lgkmcnt(0)
	s_barrier
	s_setprio 1
	s_waitcnt lgkmcnt(0)
	s_and_b64 s[100:101], s[42:43], exec
	s_cbranch_scc0 .Lkr_skip1
	v_mfma_f32_16x16x32_bf16 v[124:127], v[128:131], v[192:195], v[124:127]
	v_mfma_f32_16x16x32_bf16 v[120:123], v[160:163], v[192:195], v[120:123]
	v_mfma_f32_16x16x32_bf16 v[116:119], v[128:131], v[200:203], v[116:119]
	v_mfma_f32_16x16x32_bf16 v[108:111], v[160:163], v[200:203], v[108:111]
	v_mfma_f32_16x16x32_bf16 v[100:103], v[128:131], v[210:213], v[100:103]
	v_mfma_f32_16x16x32_bf16 v[92:95], v[160:163], v[210:213], v[92:95]
	v_mfma_f32_16x16x32_bf16 v[84:87], v[128:131], v[218:221], v[84:87]
	v_mfma_f32_16x16x32_bf16 v[76:79], v[160:163], v[218:221], v[76:79]
	v_mfma_f32_16x16x32_bf16 v[124:127], v[132:135], v[196:199], v[124:127]
	v_mfma_f32_16x16x32_bf16 v[120:123], v[164:167], v[196:199], v[120:123]
	v_mfma_f32_16x16x32_bf16 v[116:119], v[132:135], v[206:209], v[116:119]
	v_mfma_f32_16x16x32_bf16 v[108:111], v[164:167], v[206:209], v[108:111]
	v_mfma_f32_16x16x32_bf16 v[100:103], v[132:135], v[214:217], v[100:103]
	v_mfma_f32_16x16x32_bf16 v[92:95], v[164:167], v[214:217], v[92:95]
	v_mfma_f32_16x16x32_bf16 v[84:87], v[132:135], v[222:225], v[84:87]
	v_mfma_f32_16x16x32_bf16 v[76:79], v[164:167], v[222:225], v[76:79]
.Lkr_skip1:
	s_setprio 0
	s_setprio 1
	s_and_b64 s[100:101], s[42:43], exec
	s_cbranch_scc0 .Lkr_skip2
.Lkr_skip2:
	s_setprio 0
	s_barrier
	s_add_i32 s11, s87, s3
	v_lshl_add_u64 v[168:169], s[78:79], 0, v[138:139]
	s_mov_b32 m0, s11
	ds_read_b128 v[192:195], v173 offset:16384
	ds_read_b128 v[196:199], v173 offset:17408
	ds_read_b128 v[200:203], v173 offset:18432
	ds_read_b128 v[206:209], v173 offset:19456
	ds_read_b128 v[210:213], v173 offset:20480
	ds_read_b128 v[214:217], v173 offset:21504
	ds_read_b128 v[218:221], v173 offset:22528
	ds_read_b128 v[222:225], v173 offset:23552
	global_load_lds_dwordx4 v[168:169], off
	s_add_i32 m0, s11, 0x2000
	s_add_u32 s60, s78, 0x80000
	v_lshl_add_u64 v[226:227], s[78:79], 0, v[142:143]
	s_addc_u32 s61, s79, 0
	s_add_i32 s11, s91, s3
	global_load_lds_dwordx4 v[226:227], off
	v_lshl_add_u64 v[228:229], s[60:61], 0, v[138:139]
	s_mov_b32 m0, s11
	v_lshl_add_u64 v[230:231], s[80:81], 0, v[140:141]
	global_load_lds_dwordx4 v[228:229], off
	v_lshl_add_u64 v[228:229], s[60:61], 0, v[142:143]
	s_add_i32 m0, s11, 0x2000
	s_nop 0
	global_load_lds_dwordx4 v[228:229], off
	v_lshl_add_u64 v[228:229], s[80:81], 0, v[136:137]
	s_mov_b32 m0, s82
	s_nop 0
	global_load_lds_dwordx4 v[228:229], off
	s_mov_b32 m0, s83
	s_nop 0
	global_load_lds_dwordx4 v[230:231], off
	s_waitcnt vmcnt(8)
	s_waitcnt lgkmcnt(0)
	s_barrier
	s_setprio 1
	s_waitcnt lgkmcnt(0)
	s_and_b64 s[100:101], s[42:43], exec
	s_cbranch_scc0 .Lkr_skip3
	v_mfma_f32_16x16x32_bf16 v[60:63], v[128:131], v[192:195], v[60:63]
	v_mfma_f32_16x16x32_bf16 v[56:59], v[160:163], v[192:195], v[56:59]
	v_mfma_f32_16x16x32_bf16 v[52:55], v[128:131], v[200:203], v[52:55]
	v_mfma_f32_16x16x32_bf16 v[44:47], v[160:163], v[200:203], v[44:47]
	v_mfma_f32_16x16x32_bf16 v[36:39], v[128:131], v[210:213], v[36:39]
	v_mfma_f32_16x16x32_bf16 v[28:31], v[160:163], v[210:213], v[28:31]
	v_mfma_f32_16x16x32_bf16 v[20:23], v[128:131], v[218:221], v[20:23]
	v_mfma_f32_16x16x32_bf16 v[12:15], v[160:163], v[218:221], v[12:15]
	v_mfma_f32_16x16x32_bf16 v[60:63], v[132:135], v[196:199], v[60:63]
	v_mfma_f32_16x16x32_bf16 v[56:59], v[164:167], v[196:199], v[56:59]
	v_mfma_f32_16x16x32_bf16 v[52:55], v[132:135], v[206:209], v[52:55]
	v_mfma_f32_16x16x32_bf16 v[44:47], v[164:167], v[206:209], v[44:47]
	v_mfma_f32_16x16x32_bf16 v[36:39], v[132:135], v[214:217], v[36:39]
	v_mfma_f32_16x16x32_bf16 v[28:31], v[164:167], v[214:217], v[28:31]
	v_mfma_f32_16x16x32_bf16 v[20:23], v[132:135], v[222:225], v[20:23]
	v_mfma_f32_16x16x32_bf16 v[12:15], v[164:167], v[222:225], v[12:15]

.Lkr_skip4:
	s_setprio 0
	s_barrier
	s_add_i32 s11, 0, 0x18000
	v_add_u32_e32 v144, s11, v170
	s_add_i32 s62, 0, 0x1c000
	ds_read_b128 v[128:131], v144
	ds_read_b128 v[132:135], v144 offset:1024
	ds_read_b128 v[160:163], v144 offset:2048
	ds_read_b128 v[164:167], v144 offset:3072
	v_add_u32_e32 v144, s62, v170
	ds_read_b128 v[176:179], v144
	ds_read_b128 v[180:183], v144 offset:1024
	ds_read_b128 v[184:187], v144 offset:2048
	ds_read_b128 v[188:191], v144 offset:3072
	s_add_u32 s60, s80, 0x80000
	s_addc_u32 s61, s81, 0
	s_mov_b32 m0, s84
	v_lshl_add_u64 v[232:233], s[60:61], 0, v[136:137]
	ds_read_b128 v[192:195], v173 offset:32768
	ds_read_b128 v[196:199], v173 offset:33792
	ds_read_b128 v[200:203], v173 offset:34816
	ds_read_b128 v[206:209], v173 offset:35840
	ds_read_b128 v[210:213], v173 offset:36864
	ds_read_b128 v[214:217], v173 offset:37888
	ds_read_b128 v[218:221], v173 offset:38912
	ds_read_b128 v[222:225], v173 offset:39936
	global_load_lds_dwordx4 v[232:233], off
	v_lshl_add_u64 v[232:233], s[60:61], 0, v[140:141]
	s_mov_b32 m0, s85
	s_nop 0
	global_load_lds_dwordx4 v[232:233], off
	s_waitcnt vmcnt(8)
	s_waitcnt lgkmcnt(0)
	s_barrier
	s_setprio 1
	s_waitcnt lgkmcnt(0)
	s_and_b64 s[100:101], s[42:43], exec
	s_cbranch_scc0 .Lkr_skip5
	v_mfma_f32_16x16x32_bf16 v[124:127], v[128:131], v[192:195], v[124:127]
	v_mfma_f32_16x16x32_bf16 v[120:123], v[160:163], v[192:195], v[120:123]
	v_mfma_f32_16x16x32_bf16 v[116:119], v[128:131], v[200:203], v[116:119]
	v_mfma_f32_16x16x32_bf16 v[108:111], v[160:163], v[200:203], v[108:111]
	v_mfma_f32_16x16x32_bf16 v[100:103], v[128:131], v[210:213], v[100:103]
	v_mfma_f32_16x16x32_bf16 v[92:95], v[160:163], v[210:213], v[92:95]
	v_mfma_f32_16x16x32_bf16 v[84:87], v[128:131], v[218:221], v[84:87]
	v_mfma_f32_16x16x32_bf16 v[76:79], v[160:163], v[218:221], v[76:79]
	v_mfma_f32_16x16x32_bf16 v[124:127], v[132:135], v[196:199], v[124:127]
	v_mfma_f32_16x16x32_bf16 v[120:123], v[164:167], v[196:199], v[120:123]
	v_mfma_f32_16x16x32_bf16 v[116:119], v[132:135], v[206:209], v[116:119]
	v_mfma_f32_16x16x32_bf16 v[108:111], v[164:167], v[206:209], v[108:111]
	v_mfma_f32_16x16x32_bf16 v[100:103], v[132:135], v[214:217], v[100:103]
	v_mfma_f32_16x16x32_bf16 v[92:95], v[164:167], v[214:217], v[92:95]
	v_mfma_f32_16x16x32_bf16 v[84:87], v[132:135], v[222:225], v[84:87]
	v_mfma_f32_16x16x32_bf16 v[76:79], v[164:167], v[222:225], v[76:79]

.Lkr_skip6:
	s_setprio 0
	s_barrier
	s_add_i32 s11, s11, s3
	v_lshl_add_u64 v[168:169], v[168:169], 0, s[38:39]
	s_mov_b32 m0, s11
	ds_read_b128 v[192:195], v173 offset:49152
	ds_read_b128 v[196:199], v173 offset:50176
	ds_read_b128 v[200:203], v173 offset:51200
	ds_read_b128 v[206:209], v173 offset:52224
	ds_read_b128 v[210:213], v173 offset:53248
	ds_read_b128 v[214:217], v173 offset:54272
	ds_read_b128 v[218:221], v173 offset:55296
	ds_read_b128 v[222:225], v173 offset:56320
	global_load_lds_dwordx4 v[168:169], off
	s_add_i32 m0, s11, 0x2000
	s_add_u32 s60, s78, 0x80080
	v_lshl_add_u64 v[168:169], v[226:227], 0, s[38:39]
	s_addc_u32 s61, s79, 0
	s_add_i32 s11, s62, s3
	global_load_lds_dwordx4 v[168:169], off
	v_lshl_add_u64 v[168:169], s[60:61], 0, v[138:139]
	s_mov_b32 m0, s11
	s_nop 0
	global_load_lds_dwordx4 v[168:169], off
	v_lshl_add_u64 v[168:169], s[60:61], 0, v[142:143]
	s_add_i32 m0, s11, 0x2000
	s_nop 0
	global_load_lds_dwordx4 v[168:169], off
	v_lshl_add_u64 v[168:169], v[228:229], 0, s[38:39]
	s_mov_b32 m0, s89
	s_nop 0
	global_load_lds_dwordx4 v[168:169], off
	v_lshl_add_u64 v[168:169], v[230:231], 0, s[38:39]
	s_mov_b32 m0, s90
	s_nop 0
	global_load_lds_dwordx4 v[168:169], off
	s_waitcnt vmcnt(8)
	s_waitcnt lgkmcnt(0)
	s_barrier
	s_setprio 1
	s_waitcnt lgkmcnt(0)
	s_and_b64 s[100:101], s[42:43], exec
	s_cbranch_scc0 .Lkr_skip7
	v_mfma_f32_16x16x32_bf16 v[60:63], v[128:131], v[192:195], v[60:63]
	v_mfma_f32_16x16x32_bf16 v[56:59], v[160:163], v[192:195], v[56:59]
	v_mfma_f32_16x16x32_bf16 v[52:55], v[128:131], v[200:203], v[52:55]
	v_mfma_f32_16x16x32_bf16 v[44:47], v[160:163], v[200:203], v[44:47]
	v_mfma_f32_16x16x32_bf16 v[36:39], v[128:131], v[210:213], v[36:39]
	v_mfma_f32_16x16x32_bf16 v[28:31], v[160:163], v[210:213], v[28:31]
	v_mfma_f32_16x16x32_bf16 v[20:23], v[128:131], v[218:221], v[20:23]
	v_mfma_f32_16x16x32_bf16 v[12:15], v[160:163], v[218:221], v[12:15]
	v_mfma_f32_16x16x32_bf16 v[60:63], v[132:135], v[196:199], v[60:63]
	v_mfma_f32_16x16x32_bf16 v[56:59], v[164:167], v[196:199], v[56:59]
	v_mfma_f32_16x16x32_bf16 v[52:55], v[132:135], v[206:209], v[52:55]
	v_mfma_f32_16x16x32_bf16 v[44:47], v[164:167], v[206:209], v[44:47]
	v_mfma_f32_16x16x32_bf16 v[36:39], v[132:135], v[214:217], v[36:39]
	v_mfma_f32_16x16x32_bf16 v[28:31], v[164:167], v[214:217], v[28:31]
	v_mfma_f32_16x16x32_bf16 v[20:23], v[132:135], v[222:225], v[20:23]
	v_mfma_f32_16x16x32_bf16 v[12:15], v[164:167], v[222:225], v[12:15]

.Lkr_skip8:
	s_setprio 0
	s_barrier
	s_add_i32 s10, s10, 2
	s_add_u32 s76, s76, 0x100
	s_addc_u32 s77, s77, 0
	s_add_u32 vcc_lo, vcc_lo, 0x100
	s_addc_u32 vcc_hi, vcc_hi, 0
	s_cmp_gt_u32 s10, 29
	s_cbranch_scc0 .Lkr_loop
	s_branch .Lkr_ret
